# phase-4/5 wave priority: moba and mLSTM-out waves at s_setprio 1, scan and the barrier-5 hidden weight-conversion waves at 0
# speedup vs baseline: 1.0046x; 1.0036x over previous
.LBB0_724:
	s_setprio 0
	s_waitcnt vmcnt(0)
	s_barrier
	s_mov_b64 s[4:5], exec
	v_readlane_b32 s0, v255, 1
	v_readlane_b32 s1, v255, 2
	s_and_b64 s[0:1], s[4:5], s[0:1]
	s_mov_b64 exec, s[0:1]
	s_cbranch_execz .LBB0_776
	v_readlane_b32 s98, v255, 5
	v_readlane_b32 s99, v255, 6
	s_nop 3
	s_lshl_b32 s0, s3, 8
	s_add_u32 s100, s98, s0
	s_addc_u32 s101, s99, 0
	v_mov_b32_e32 v19, 0x10000
	s_waitcnt vmcnt(0) expcnt(0) lgkmcnt(0)
	ds_read_b32 v2, v19
	v_mov_b32_e32 v19, 0x10004
	ds_read_b32 v5, v19
	v_mov_b32_e32 v3, 0x1000
	v_mov_b32_e32 v4, 1
	global_atomic_add v3, v3, v4, s[100:101] offset:1024 sc0
	s_waitcnt vmcnt(0) lgkmcnt(0)
	v_add_u32_e32 v3, 1, v3
	v_mul_u32_u24_e32 v6, 4, v2
	v_add_u32_e32 v6, 1, v6
	v_cmp_eq_u32_e32 vcc, v3, v6
	s_cbranch_vccz .Lgb5_nf
	buffer_wbl2 sc1
